# v12 + 4096 layer-1 fp8 weight-conversion items moved from layer 0's branch tail (6->4 rounds) into layer 0's in-proj phase (workgroups 105..207, idle there)
# baseline (speedup 1.0000x reference)
.LBB0_80:
	v_readlane_b32 s22, v248, 1
	v_readlane_b32 s23, v248, 2
	s_add_u32 s0, s22, 0x72d00000
	s_addc_u32 s1, s23, 0
	v_writelane_b32 v249, s0, 4
	v_readlane_b32 s24, v248, 7
	v_readlane_b32 s48, v248, 26
	v_writelane_b32 v249, s1, 5
	s_ashr_i32 s0, s24, 31
	v_readlane_b32 s50, v248, 28
	v_writelane_b32 v249, s0, 6
	v_readlane_b32 s51, v248, 29
	s_add_u32 s0, s50, 0x2000
	s_addc_u32 s1, s51, 0
	v_writelane_b32 v249, s0, 7
	s_cmpk_lg_i32 s24, 0x100
	v_readlane_b32 s13, v248, 43
	v_writelane_b32 v249, s1, 8
	s_cselect_b64 s[0:1], -1, 0
	v_writelane_b32 v249, s0, 9
	s_cmpk_lt_i32 s13, 0x1400
	v_readlane_b32 s21, v248, 0
	v_writelane_b32 v249, s1, 10
	s_cselect_b64 s[0:1], -1, 0
	v_writelane_b32 v249, s0, 11
	v_readlane_b32 s49, v248, 27
	v_mov_b32_e32 v34, 0
	v_writelane_b32 v249, s1, 12
	s_add_i32 s0, s13, 0x3c80
	s_add_u32 s9, s22, 0x24500000
	s_addc_u32 s12, s23, 0
	s_add_u32 s5, s22, 0x1e500000
	v_writelane_b32 v249, s0, 13
	s_addc_u32 s11, s23, 0
	s_add_i32 s0, s21, 0xffffff97
	s_cmpk_lt_u32 s0, 0x67
	s_cselect_b64 s[0:1], -1, 0
	v_writelane_b32 v249, s0, 14
	v_mov_b32_e32 v219, 1
	v_mov_b32_e32 v222, 0x358637bd
	v_writelane_b32 v249, s1, 15
	s_add_i32 s0, s13, 0xfffffcb8
	s_cmpk_lt_i32 s0, 0x1400
	s_cselect_b64 s[0:1], -1, 0
	v_writelane_b32 v249, s0, 16
	v_mov_b32_e32 v223, 0x260
	v_mov_b32_e32 v224, 0x3ecc95a3
	v_writelane_b32 v249, s1, 17
	s_add_i32 s0, s13, 0x3938
	v_writelane_b32 v249, s0, 18
	s_add_u32 s0, s22, 0x4200
	s_addc_u32 s1, s23, 0
	v_writelane_b32 v249, s0, 19
	v_mov_b32_e32 v225, 0x3e2aaaab
	v_mov_b64_e32 v[164:165], 0x969
	v_writelane_b32 v249, s1, 20
	s_add_u32 s0, s22, 0x4400
	s_addc_u32 s1, s23, 0
	v_writelane_b32 v249, s0, 21
	v_mov_b64_e32 v[166:167], 0x968
	v_mov_b32_e32 v226, 0x41b17218
	v_writelane_b32 v249, s1, 22
	s_add_u32 s0, s22, 0x4500
	s_addc_u32 s1, s23, 0
	v_writelane_b32 v249, s0, 23
	v_mov_b64_e32 v[168:169], 0x630
	v_mov_b64_e32 v[170:171], 0x62f
	v_writelane_b32 v249, s1, 24
	s_add_u32 s0, s22, 0x4600
	s_addc_u32 s1, s23, 0
	v_writelane_b32 v249, s0, 25
	v_mov_b32_e32 v227, 0x1e040
	v_mov_b32_e32 v228, 2
	v_writelane_b32 v249, s1, 26
	s_add_u32 s0, s22, 0x4700
	s_addc_u32 s1, s23, 0
	v_writelane_b32 v249, s0, 27
	v_mov_b32_e32 v230, 0x3000
	v_mov_b32_e32 v231, 0x7f800000
	v_writelane_b32 v249, s1, 28
	s_add_u32 s0, s22, 0x4800
	s_addc_u32 s1, s23, 0
	v_writelane_b32 v249, s0, 29
	v_readlane_b32 s52, v248, 30
	v_readlane_b32 s53, v248, 31
	v_writelane_b32 v249, s1, 30
	s_add_u32 s0, s22, 0x4900
	s_addc_u32 s1, s23, 0
	v_writelane_b32 v249, s0, 31
	v_readlane_b32 s54, v248, 32
	v_readlane_b32 s55, v248, 33
	v_writelane_b32 v249, s1, 32
	s_add_u32 s0, s22, 0x4a00
	s_addc_u32 s1, s23, 0
	v_writelane_b32 v249, s0, 33
	v_readlane_b32 s56, v248, 34
	v_readlane_b32 s57, v248, 35
	v_writelane_b32 v249, s1, 34
	s_add_u32 s0, s22, 0x4b00
	s_addc_u32 s1, s23, 0
	v_writelane_b32 v249, s0, 35
	v_readlane_b32 s58, v248, 36
	v_readlane_b32 s59, v248, 37
	v_writelane_b32 v249, s1, 36
	s_add_u32 s0, s22, 0x4c00
	s_addc_u32 s1, s23, 0
	v_writelane_b32 v249, s0, 37
	v_readlane_b32 s60, v248, 38
	v_readlane_b32 s61, v248, 39
	v_writelane_b32 v249, s1, 38
	s_add_u32 s0, s22, 0x4d00
	s_addc_u32 s1, s23, 0
	v_writelane_b32 v249, s0, 39
	v_readlane_b32 s62, v248, 40
	v_readlane_b32 s63, v248, 41
	v_writelane_b32 v249, s1, 40
	s_add_u32 s0, s22, 0x4e00
	s_addc_u32 s1, s23, 0
	v_writelane_b32 v249, s0, 41
	s_nop 1
	v_writelane_b32 v249, s1, 42
	s_add_u32 s0, s22, 0x4f00
	s_addc_u32 s1, s23, 0
	v_writelane_b32 v249, s0, 43
	s_nop 1
	v_writelane_b32 v249, s1, 44
	s_add_u32 s0, s22, 0x5000
	s_addc_u32 s1, s23, 0
	v_writelane_b32 v249, s0, 45
	s_nop 1
	v_writelane_b32 v249, s1, 46
	s_add_u32 s0, s22, 0x5100
	s_addc_u32 s1, s23, 0
	v_writelane_b32 v249, s0, 47
	s_nop 1
	v_writelane_b32 v249, s1, 48
	s_add_u32 s0, s22, 0x5200
	s_addc_u32 s1, s23, 0
	v_writelane_b32 v249, s0, 49
	s_nop 1
	v_writelane_b32 v249, s1, 50
	s_add_u32 s0, s22, 0x5300
	s_addc_u32 s1, s23, 0
	v_writelane_b32 v249, s0, 51
	s_cmp_eq_u32 s46, 15
	s_nop 0
	v_writelane_b32 v249, s1, 52
	s_cselect_b64 s[0:1], -1, 0
	v_writelane_b32 v249, s0, 53
	s_cmp_eq_u32 s46, 14
	s_nop 0
	v_writelane_b32 v249, s1, 54
	s_cselect_b64 s[0:1], -1, 0
	v_writelane_b32 v249, s0, 55
	s_cmp_eq_u32 s46, 13
	s_nop 0
	v_writelane_b32 v249, s1, 56
	s_cselect_b64 s[0:1], -1, 0
	v_writelane_b32 v249, s0, 57
	s_cmp_eq_u32 s46, 12
	s_nop 0
	v_writelane_b32 v249, s1, 58
	s_cselect_b64 s[0:1], -1, 0
	v_writelane_b32 v249, s0, 59
	s_cmp_eq_u32 s46, 11
	s_nop 0
	v_writelane_b32 v249, s1, 60
	s_cselect_b64 s[0:1], -1, 0
	v_writelane_b32 v249, s0, 61
	s_cmp_eq_u32 s46, 10
	s_nop 0
	v_writelane_b32 v249, s1, 62
	s_cselect_b64 s[0:1], -1, 0
	v_writelane_b32 v249, s0, 63
	s_cmp_eq_u32 s46, 9
	s_nop 0
	v_writelane_b32 v250, s1, 0
	s_cselect_b64 s[0:1], -1, 0
	v_writelane_b32 v250, s0, 1
	s_cmp_eq_u32 s46, 8
	s_nop 0
	v_writelane_b32 v250, s1, 2
	s_cselect_b64 s[0:1], -1, 0
	v_writelane_b32 v250, s0, 3
	s_cmp_eq_u32 s46, 7
	s_nop 0
	v_writelane_b32 v250, s1, 4
	s_cselect_b64 s[0:1], -1, 0
	v_writelane_b32 v250, s0, 5
	s_cmp_eq_u32 s46, 6
	s_nop 0
	v_writelane_b32 v250, s1, 6
	s_cselect_b64 s[0:1], -1, 0
	v_writelane_b32 v250, s0, 7
	s_cmp_eq_u32 s46, 5
	s_nop 0
	v_writelane_b32 v250, s1, 8
	s_cselect_b64 s[0:1], -1, 0
	v_writelane_b32 v250, s0, 9
	s_cmp_eq_u32 s46, 4
	s_nop 0
	v_writelane_b32 v250, s1, 10
	s_cselect_b64 s[0:1], -1, 0
	v_writelane_b32 v250, s0, 11
	s_cmp_eq_u32 s46, 3
	s_nop 0
	v_writelane_b32 v250, s1, 12
	s_cselect_b64 s[0:1], -1, 0
	v_writelane_b32 v250, s0, 13
	s_cmp_eq_u32 s46, 2
	s_nop 0
	v_writelane_b32 v250, s1, 14
	s_cselect_b64 s[0:1], -1, 0
	v_writelane_b32 v250, s0, 15
	s_cmp_eq_u32 s46, 1
	s_nop 0
	v_writelane_b32 v250, s1, 16
	s_cselect_b64 s[0:1], -1, 0
	v_writelane_b32 v250, s0, 17
	s_cmp_eq_u32 s46, 0
	s_nop 0
	v_writelane_b32 v250, s1, 18
	s_cselect_b64 s[0:1], -1, 0
	v_writelane_b32 v250, s0, 19
	s_nop 1
	v_writelane_b32 v250, s1, 20
	s_lshl_b32 s0, s46, 8
	s_add_u32 s0, s2, s0
	s_addc_u32 s1, s3, 0
	s_add_u32 s2, s0, 0x1400
	s_addc_u32 s3, s1, 0
	v_writelane_b32 v250, s2, 21
	s_add_u32 s0, s0, 0x2400
	s_addc_u32 s1, s1, 0
	v_writelane_b32 v250, s3, 22
	v_writelane_b32 v250, s0, 23
	s_nop 1
	v_writelane_b32 v250, s1, 24
	s_add_u32 s0, s22, 0x7400
	s_addc_u32 s1, s23, 0
	v_writelane_b32 v250, s0, 25
	s_nop 1
	v_writelane_b32 v250, s1, 26
	s_add_u32 s0, s22, 0x7500
	s_addc_u32 s1, s23, 0
	v_writelane_b32 v250, s0, 27
	s_cmpk_lt_i32 s21, 0x220
	s_nop 0
	v_writelane_b32 v250, s1, 28
	s_cselect_b64 s[0:1], -1, 0
	v_writelane_b32 v250, s0, 29
	s_ashr_i32 s14, s21, 31
	s_add_i32 s8, s21, 0xffffff40
	v_writelane_b32 v250, s1, 30
	s_lshr_b32 s0, s14, 26
	s_add_i32 s0, s21, s0
	s_ashr_i32 s7, s0, 6
	s_add_i32 s0, s24, 0xffffff40
	v_writelane_b32 v250, s0, 31
	s_sub_i32 s0, s21, 64
	s_cmpk_lt_i32 s21, 0x80
	s_cselect_b32 s25, s21, s0
	s_cmpk_lt_i32 s25, 0x220
	v_writelane_b32 v250, s0, 32
	s_cselect_b64 s[0:1], -1, 0
	v_writelane_b32 v250, s0, 33
	s_nop 1
	v_writelane_b32 v250, s1, 34
	s_add_u32 s0, s22, 0x12000
	v_writelane_b32 v250, s0, 35
	s_addc_u32 s0, s23, 0
	v_writelane_b32 v250, s0, 36
	s_add_i32 s0, s21, 0xffffff80
	v_writelane_b32 v250, s0, 37
	s_add_i32 s0, s21, 1
	v_writelane_b32 v250, s0, 38
	s_sub_i32 s0, s21, 63
	v_writelane_b32 v250, s0, 39
	s_add_i32 s0, s21, 0xffffff81
	s_cmpk_gt_i32 s21, 0xbf
	v_writelane_b32 v250, s0, 40
	s_cselect_b64 s[0:1], -1, 0
	s_cmpk_eq_i32 s24, 0x100
	s_cselect_b64 s[26:27], -1, 0
	s_and_b64 s[2:3], s[26:27], exec
	s_movk_i32 s2, 0x200
	s_cselect_b32 s6, s2, 0x210
	s_movk_i32 s2, 0x2000
	s_cselect_b32 s2, s2, 0x2100
	v_writelane_b32 v250, s2, 41
	s_cselect_b32 s19, 32, 33
	s_cselect_b32 s10, 0xc80, 0
	s_and_b64 s[0:1], s[0:1], s[26:27]
	v_writelane_b32 v250, s0, 42
	s_nop 1
	v_writelane_b32 v250, s1, 43
	s_add_u32 s0, s22, 0x10000
	v_writelane_b32 v250, s0, 44
	s_addc_u32 s0, s23, 0
	v_writelane_b32 v250, s0, 45
	s_lshl_b32 s0, s8, 3
	s_add_i32 s15, s33, s0
	s_cmpk_lt_i32 s21, 0xf0
	s_mul_hi_i32 s0, s8, 0x55555556
	s_cselect_b64 s[2:3], -1, 0
	s_lshr_b32 s1, s0, 31
	s_add_i32 s1, s0, s1
	s_mul_i32 s0, s1, -3
	v_writelane_b32 v250, s2, 46
	s_add_i32 s0, s0, s8
	s_mul_i32 s4, s1, 0x300000
	v_writelane_b32 v250, s3, 47
	s_lshl_b32 s2, s0, 11
	s_ashr_i32 s3, s2, 31
	s_lshl_b64 s[28:29], s[2:3], 1
	s_add_u32 s2, s5, s28
	v_writelane_b32 v250, s5, 48
	s_addc_u32 s3, s11, s29
	v_writelane_b32 v250, s11, 49
	s_add_u32 s2, s2, s4
	s_mul_hi_i32 s5, s1, 0x300000
	v_writelane_b32 v250, s2, 50
	s_addc_u32 s2, s3, s5
	v_writelane_b32 v250, s2, 51
	s_lshl_b32 s1, s1, 8
	v_writelane_b32 v250, s1, 52
	s_ashr_i32 s1, s0, 31
	s_lshl_b64 s[2:3], s[0:1], 12
	v_writelane_b32 v250, s2, 53
	s_lshl_b64 s[0:1], s[0:1], 22
	s_ashr_i32 s8, s8, 2
	v_writelane_b32 v250, s3, 54
	v_writelane_b32 v250, s0, 55
	s_nop 1
	v_writelane_b32 v250, s1, 56
	s_and_b32 s0, s21, 3
	s_lshl_b32 s2, s0, 10
	s_lshl_b32 s30, s0, 11
	v_writelane_b32 v250, s9, 57
	s_add_u32 s11, s9, s30
	v_writelane_b32 v250, s12, 58
	s_addc_u32 s12, s12, 0
	s_ashr_i32 s9, s8, 31
	s_lshl_b32 s3, s0, 20
	s_lshl_b64 s[0:1], s[8:9], 21
	s_add_u32 s9, s11, s0
	v_writelane_b32 v250, s9, 59
	s_addc_u32 s9, s12, s1
	v_writelane_b32 v250, s9, 60
	s_lshl_b32 s8, s8, 8
	v_writelane_b32 v250, s8, 61
	s_cmpk_lt_i32 s15, 0xc80
	v_writelane_b32 v250, s15, 62
	s_cselect_b64 s[8:9], -1, 0
	v_writelane_b32 v250, s8, 63
	s_nop 1
	v_writelane_b32 v251, s9, 0
	s_add_u32 s8, s48, 0x1e040000
	s_addc_u32 s9, s49, 0
	v_writelane_b32 v251, s8, 1
	v_readlane_b32 s36, v248, 10
	v_readlane_b32 s50, v248, 24
	v_writelane_b32 v251, s9, 2
	s_add_u32 s8, s22, 0xf300000
	s_addc_u32 s9, s23, 0
	s_lshl_b32 s34, s19, 4
	v_writelane_b32 v251, s8, 3
	s_cmp_lt_i32 s21, s34
	v_readlane_b32 s51, v248, 25
	v_writelane_b32 v251, s9, 4
	s_cselect_b64 s[8:9], -1, 0
	v_writelane_b32 v251, s8, 5
	s_add_i32 s16, s24, s6
	s_add_i32 s20, s19, -8
	v_writelane_b32 v251, s9, 6
	s_lshr_b32 s8, s14, 29
	s_add_i32 s8, s21, s8
	v_writelane_b32 v251, s14, 7
	s_ashr_i32 s14, s8, 3
	s_and_b32 s8, s8, -8
	s_sub_i32 s15, s21, s8
	s_add_i32 s17, s16, -1
	s_add_i32 s8, s13, s10
	s_cmpk_lt_i32 s8, 0x2c80
	v_writelane_b32 v251, s8, 8
	s_cselect_b64 s[8:9], -1, 0
	v_writelane_b32 v251, s8, 9
	v_readlane_b32 s48, v248, 22
	v_readlane_b32 s49, v248, 23
	v_writelane_b32 v251, s9, 10
	s_add_u32 s8, s22, 0x85300000
	s_addc_u32 s9, s23, 0
	s_lshl_b32 s31, s19, 1
	v_writelane_b32 v251, s8, 11
	s_add_i32 s18, s10, s33
	s_or_b32 s33, s31, 1
	v_writelane_b32 v251, s9, 12
	s_add_u32 s8, s22, 0x76d00000
	v_writelane_b32 v251, s8, 13
	s_addc_u32 s8, s23, 0
	v_writelane_b32 v251, s8, 14
	s_add_u32 s8, s50, 0x4000
	s_addc_u32 s9, s51, 0
	v_writelane_b32 v251, s8, 15
	v_mov_b32_e32 v1, s15
	v_alignbit_b32 v1, s19, v1, 31
	v_writelane_b32 v251, s9, 16
	s_add_u32 s8, s48, 0x4000
	s_addc_u32 s9, s49, 0
	v_writelane_b32 v251, s8, 17
	v_readlane_b32 s37, v248, 11
	v_readlane_b32 s38, v248, 12
	v_writelane_b32 v251, s9, 18
	v_readlane_b32 s8, v248, 3
	v_readlane_b32 s9, v248, 4
	s_mov_b64 s[12:13], s[8:9]
	s_cmp_gt_i32 s12, 7
	v_readlane_b32 s10, v248, 5
	v_readlane_b32 s11, v248, 6
	s_cselect_b64 s[8:9], -1, 0
	s_cmp_lt_i32 s13, 9
	s_cselect_b64 s[10:11], -1, 0
	s_cmpk_lt_i32 s21, 0xc0
	s_cselect_b32 s7, s7, -1
	s_cmpk_gt_i32 s24, 0xc0
	s_cselect_b32 s7, s7, -2
	s_cmp_lg_u32 s7, 2
	s_cselect_b64 s[12:13], -1, 0
	v_writelane_b32 v251, s26, 19
	s_and_b64 s[12:13], s[26:27], s[12:13]
	s_cmp_lg_u32 s7, 1
	v_writelane_b32 v251, s27, 20
	v_writelane_b32 v251, s12, 21
	v_readlane_b32 s39, v248, 13
	v_readlane_b32 s40, v248, 14
	v_writelane_b32 v251, s13, 22
	v_writelane_b32 v251, s7, 23
	v_readfirstlane_b32 s7, v1
	v_writelane_b32 v251, s19, 24
	s_mul_i32 s7, s7, s15
	s_cselect_b64 s[12:13], -1, 0
	v_writelane_b32 v251, s12, 25
	s_add_i32 s7, s7, s14
	v_readlane_b32 s41, v248, 15
	v_writelane_b32 v251, s13, 26
	s_ashr_i32 s12, s7, 31
	s_lshr_b32 s12, s12, 25
	s_add_i32 s12, s7, s12
	s_ashr_i32 s12, s12, 7
	s_lshl_b32 s13, s12, 7
	s_sub_i32 s7, s7, s13
	s_lshl_b32 s12, s12, 3
	s_cmp_gt_i32 s12, s20
	s_cselect_b32 s13, 1, 8
	s_cmp_lt_i32 s15, 0
	s_cselect_b32 s19, s33, s31
	s_mul_i32 s15, s19, s15
	s_add_i32 s14, s15, s14
	v_cvt_f32_ubyte0_e32 v1, s13
	s_ashr_i32 s15, s14, 31
	v_rcp_iflag_f32_e32 v1, v1
	s_lshr_b32 s15, s15, 25
	s_add_i32 s15, s14, s15
	s_ashr_i32 s15, s15, 7
	s_lshl_b32 s19, s15, 7
	v_mul_f32_e32 v1, 0x4f7ffffe, v1
	v_writelane_b32 v251, s31, 27
	s_sub_i32 s14, s14, s19
	s_lshl_b32 s15, s15, 3
	v_cvt_u32_f32_e32 v1, v1
	v_writelane_b32 v251, s33, 28
	s_cmp_gt_i32 s15, s20
	v_writelane_b32 v251, s20, 29
	s_cselect_b32 s19, 1, 8
	s_or_b64 s[8:9], s[8:9], s[10:11]
	v_writelane_b32 v251, s8, 30
	s_mov_b32 s33, 0xbcf5c28f
	v_readlane_b32 s42, v248, 16
	v_writelane_b32 v251, s9, 31
	s_sub_i32 s8, 0, s13
	v_readfirstlane_b32 s9, v1
	s_mul_i32 s8, s8, s9
	s_mul_hi_u32 s8, s9, s8
	s_add_i32 s9, s9, s8
	s_abs_i32 s8, s7
	s_mul_hi_u32 s9, s8, s9
	s_mul_i32 s10, s9, s13
	s_sub_i32 s8, s8, s10
	s_ashr_i32 s10, s7, 31
	s_add_i32 s11, s9, 1
	s_sub_i32 s20, s8, s13
	s_cmp_ge_u32 s8, s13
	s_cselect_b32 s9, s11, s9
	s_cselect_b32 s8, s20, s8
	s_add_i32 s11, s9, 1
	s_cmp_ge_u32 s8, s13
	s_cselect_b32 s8, s11, s9
	s_xor_b32 s8, s8, s10
	s_sub_i32 s8, s8, s10
	v_writelane_b32 v251, s8, 32
	s_mul_i32 s8, s8, s13
	s_sub_i32 s7, s7, s8
	s_add_i32 s7, s12, s7
	v_writelane_b32 v251, s7, 33
	s_abs_i32 s7, s24
	v_cvt_f32_u32_e32 v1, s7
	s_sub_i32 s8, 0, s7
	v_readlane_b32 s43, v248, 17
	v_readlane_b32 s44, v248, 18
	v_rcp_iflag_f32_e32 v1, v1
	v_readlane_b32 s45, v248, 19
	v_readlane_b32 s46, v248, 20
	v_readlane_b32 s47, v248, 21
	v_mul_f32_e32 v1, 0x4f7ffffe, v1
	v_cvt_u32_f32_e32 v1, v1
	s_nop 0
	v_readfirstlane_b32 s9, v1
	s_mul_i32 s8, s8, s9
	s_mul_hi_u32 s8, s9, s8
	s_add_i32 s9, s9, s8
	s_sub_i32 s8, 1, s16
	s_max_i32 s8, s17, s8
	s_mul_hi_u32 s9, s8, s9
	s_mul_i32 s10, s9, s7
	s_sub_i32 s8, s8, s10
	s_xor_b32 s10, s17, s24
	s_ashr_i32 s10, s10, 31
	s_add_i32 s11, s9, 1
	s_sub_i32 s12, s8, s7
	s_cmp_ge_u32 s8, s7
	s_cselect_b32 s9, s11, s9
	s_cselect_b32 s8, s12, s8
	s_add_i32 s11, s9, 1
	s_cmp_ge_u32 s8, s7
	s_cselect_b32 s7, s11, s9
	s_xor_b32 s7, s7, s10
	s_not_b32 s8, s10
	s_add_i32 s7, s8, s7
	s_mul_i32 s7, s7, s24
	s_sub_i32 s6, s6, s7
	s_sub_i32 s7, s24, s6
	v_cvt_f32_ubyte0_e32 v1, s19
	s_cmp_lt_i32 s7, 1
	v_rcp_iflag_f32_e32 v1, v1
	s_cselect_b64 s[8:9], -1, 0
	v_writelane_b32 v251, s8, 34
	s_cmp_ge_i32 s21, s6
	v_mul_f32_e32 v1, 0x4f7ffffe, v1
	v_writelane_b32 v251, s9, 35
	s_cselect_b64 s[8:9], -1, 0
	s_sub_i32 s6, s21, s6
	v_writelane_b32 v251, s8, 36
	s_lshl_b32 s6, s6, 3
	s_add_i32 s6, s18, s6
	v_writelane_b32 v251, s9, 37
	s_lshl_b32 s7, s7, 3
	v_cvt_u32_f32_e32 v1, v1
	v_writelane_b32 v251, s7, 38
	s_cmpk_lt_i32 s6, 0x3c80
	v_writelane_b32 v251, s6, 39
	s_cselect_b64 s[6:7], -1, 0
	v_writelane_b32 v251, s6, 40
	s_nop 1
	v_writelane_b32 v251, s7, 41
	s_sub_i32 s6, 0, s19
	v_readfirstlane_b32 s7, v1
	s_mul_i32 s6, s6, s7
	s_mul_hi_u32 s6, s7, s6
	s_add_i32 s7, s7, s6
	s_abs_i32 s6, s14
	s_mul_hi_u32 s7, s6, s7
	s_mul_i32 s8, s7, s19
	s_sub_i32 s6, s6, s8
	s_ashr_i32 s8, s14, 31
	s_add_i32 s9, s7, 1
	s_sub_i32 s10, s6, s19
	s_cmp_ge_u32 s6, s19
	s_cselect_b32 s7, s9, s7
	s_cselect_b32 s6, s10, s6
	s_add_i32 s9, s7, 1
	s_cmp_ge_u32 s6, s19
	s_cselect_b32 s6, s9, s7
	s_xor_b32 s6, s6, s8
	s_sub_i32 s8, s6, s8
	s_mul_i32 s6, s8, s19
	s_sub_i32 s6, s14, s6
	s_add_i32 s10, s15, s6
	s_lshl_b32 s6, s21, 8
	v_writelane_b32 v251, s6, 42
	s_lshl_b32 s6, s24, 8
	v_writelane_b32 v251, s6, 43
	v_writelane_b32 v251, s25, 44
	s_lshl_b32 s6, s25, 8
	v_writelane_b32 v251, s6, 45
	s_mov_b32 s6, s10
	s_ashr_i32 s11, s10, 31
	v_writelane_b32 v251, s6, 46
	s_ashr_i32 s9, s8, 31
	v_mbcnt_lo_u32_b32 v1, -1, 0
	v_writelane_b32 v251, s7, 47
	s_lshl_b64 s[6:7], s[10:11], 21
	v_writelane_b32 v251, s6, 48
	v_mbcnt_hi_u32_b32 v229, -1, v1
	s_nop 0
	v_writelane_b32 v251, s7, 49
	s_mov_b32 s6, s8
	v_writelane_b32 v251, s6, 50
	s_nop 1
	v_writelane_b32 v251, s7, 51
	s_lshl_b64 s[6:7], s[8:9], 21
	s_add_u32 s4, s4, s28
	s_addc_u32 s5, s5, s29
	s_add_u32 s4, s22, s4
	v_writelane_b32 v251, s6, 52
	s_addc_u32 s5, s23, s5
	s_add_u32 s4, s4, 0x1e500100
	v_writelane_b32 v251, s7, 53
	v_writelane_b32 v251, s4, 54
	s_addc_u32 s4, s5, 0
	v_writelane_b32 v251, s4, 55
	s_add_u32 s4, s28, 0x55b80080
	v_writelane_b32 v251, s4, 56
	v_writelane_b32 v251, s28, 57
	s_addc_u32 s4, s29, 0
	s_or_b32 s0, s0, s30
	v_writelane_b32 v251, s29, 58
	s_mov_b32 s5, 0
	v_writelane_b32 v251, s4, 59
	s_add_u32 s0, s22, s0
	s_mov_b32 s35, s5
	s_addc_u32 s1, s23, s1
	v_writelane_b32 v251, s34, 60
	s_add_u32 s0, s0, 0x24500100
	s_mov_b64 s[6:7], -1
	v_writelane_b32 v251, s35, 61
	v_writelane_b32 v251, s0, 62
	s_addc_u32 s0, s1, 0
	v_writelane_b32 v251, s0, 63
	s_mul_hi_i32 s1, s66, 0x3000
	s_mul_i32 s0, s66, 0x3000
	v_writelane_b32 v252, s0, 0
	s_ashr_i32 s67, s66, 31
	s_mov_b32 s12, s5
	v_writelane_b32 v252, s1, 1
	s_lshl_b32 s0, s2, 1
	v_writelane_b32 v252, s0, 2
	s_lshl_b32 s0, s3, 2
	v_writelane_b32 v252, s0, 3
	v_writelane_b32 v252, s30, 4
	s_or_b32 s0, s30, 0x6a800080
	v_writelane_b32 v252, s0, 5
	s_add_i32 s0, 0, 0x19800
	v_writelane_b32 v252, s0, 6
	v_cmp_eq_u32_e64 s[0:1], 0, v0
	s_mov_b64 s[2:3], 0x80
	s_nop 0
	v_writelane_b32 v252, s0, 7
	s_nop 1
	v_writelane_b32 v252, s1, 8
	s_lshl_b64 s[0:1], s[66:67], 12
	v_writelane_b32 v252, s0, 9
	s_nop 1
	v_writelane_b32 v252, s1, 10
	s_lshl_b64 s[0:1], s[66:67], 7
	v_writelane_b32 v252, s0, 11
	s_nop 1
	v_writelane_b32 v252, s1, 12
	s_lshl_b64 s[0:1], s[66:67], 13
	v_writelane_b32 v252, s0, 13
	s_nop 1
	v_writelane_b32 v252, s1, 14
	s_mov_b32 s1, 0
	v_writelane_b32 v252, s0, 15
	s_nop 1
	v_writelane_b32 v252, s1, 16
	v_writelane_b32 v252, s66, 17
	s_nop 1
	v_writelane_b32 v252, s67, 18
	s_branch .LBB0_84

.LBB0_314:
	s_andn2_b64 vcc, exec, s[6:7]
	s_cbranch_vccnz .LBB0_343
	v_readlane_b32 s6, v249, 14
	v_readlane_b32 s7, v249, 15
	s_andn2_b64 vcc, exec, s[6:7]
	s_cbranch_vccnz .LBB0_343
	v_readlane_b32 s6, v249, 16
	v_readlane_b32 s7, v249, 17
	v_and_b32_e32 v2, 63, v0
	s_andn2_b64 vcc, exec, s[6:7]
	s_cbranch_vccnz .LBB0_343
	v_lshlrev_b32_e32 v1, 3, v2
	s_waitcnt vmcnt(0) lgkmcnt(0)
	v_lshlrev_b32_e32 v137, 4, v2
	v_readlane_b32 s13, v249, 18
	v_lshlrev_b32_e32 v7, 1, v2
	v_lshlrev_b32_e32 v35, 8, v2
	v_ashrrev_i32_e32 v136, 3, v2
	v_and_b32_e32 v6, 56, v1
	v_add_u32_e32 v138, 0x4810, v2
	v_lshlrev_b32_e32 v139, 7, v2
	v_and_b32_e32 v8, 0x70, v137
	v_mov_b32_e32 v9, v34
	s_lshl_b32 s11, s13, 7
	s_lshl_b32 s12, s13, 1
	v_readlane_b32 s98, v252, 27
	s_movk_i32 s99, 0x4d47
	s_nop 1
	s_cmp_eq_u32 s98, 0
	s_cselect_b32 s98, 0x1000, 0
	s_add_i32 s99, s99, s98
	s_mov_b32 s98, 0
	s_branch .LBB0_320

.LBB0_319:
	s_cmp_eq_u32 s98, 0
	s_cbranch_scc1 .Lcv_latch
	s_mov_b32 s13, s98
	s_mov_b32 s98, 0
	v_readlane_b32 s6, v253, 47
	v_readlane_b32 s7, v253, 48
	s_nop 1
	v_writelane_b32 v252, s6, 15
	v_writelane_b32 v252, s7, 16
	s_sub_u32 s36, s36, 0x1e040000
	s_subb_u32 s37, s37, 0
	s_sub_u32 s38, s38, 0x3000000
	s_subb_u32 s39, s39, 0
.Lcv_latch:
	s_add_i32 s6, s13, 0x338
	s_add_i32 s11, s11, 0x19c00
	s_addk_i32 s12, 0x670
	s_cmp_gt_i32 s13, s99
	s_mov_b32 s13, s6
	s_cbranch_scc1 .LBB0_343
.LBB0_320:
	s_cmpk_lt_i32 s13, 0x5080
	s_cbranch_scc1 .Lcv_norm
	s_mov_b32 s98, s13
	s_sub_i32 s13, s13, 0x2400
	v_readlane_b32 s6, v252, 15
	v_readlane_b32 s7, v252, 16
	s_nop 1
	v_writelane_b32 v253, s6, 47
	v_writelane_b32 v253, s7, 48
	s_add_u32 s36, s36, 0x1e040000
	s_addc_u32 s37, s37, 0
	s_add_u32 s38, s38, 0x3000000
	s_addc_u32 s39, s39, 0

.LBB0_1642:
	s_add_i32 s10, s10, s66
	s_add_i32 s8, s8, s9
	s_cmpk_lt_i32 s10, 0x2c80
	s_cbranch_scc0 .LBB0_1654
